# M3: workgroups that own a GLU GEMM tile take 4 rwkv_post tokens per wave, the others 9-10 (was 8 each)
# baseline (speedup 1.0000x reference)
.LBB0_1146:
	s_lshl_b32 s2, s2, 5
	s_lshl_b32 s3, s3, 2
	s_add_i32 s2, s3, s2
	s_cmp_lt_u32 s90, 64
	s_movk_i32 s20, 0x1800
	s_mov_b32 s101, 0x10000
	s_cselect_b32 s20, 0x800, s20
	s_cselect_b32 s101, 0x2000, s101
	s_cselect_b32 s21, 0, 0x1800
	s_add_i32 s2, s2, s21
	s_cmp_gt_i32 s2, 0xffff
	s_cbranch_scc1 .LBB0_1149
	s_load_dwordx2 s[16:17], s[8:9], 0x100
	s_load_dwordx4 s[12:15], s[8:9], 0xf0
	v_and_b32_e32 v0, 63, v195
	v_lshlrev_b32_e32 v2, 2, v0
	v_and_b32_e32 v4, 64, v194
	v_add_u32_e32 v4, 64, v4
	s_waitcnt lgkmcnt(0)
	global_load_dword v1, v2, s[16:17]
	global_load_dword v3, v2, s[16:17] offset:256
	global_load_dword v5, v2, s[16:17] offset:512
	global_load_dword v7, v2, s[16:17] offset:768
	global_load_dword v16, v2, s[14:15]
	global_load_dword v17, v2, s[12:13]
	global_load_dword v18, v2, s[14:15] offset:256
	global_load_dword v19, v2, s[12:13] offset:256
	global_load_dword v20, v2, s[14:15] offset:512
	global_load_dword v21, v2, s[12:13] offset:512
	global_load_dword v22, v2, s[14:15] offset:768
	global_load_dword v23, v2, s[12:13] offset:768
	v_xor_b32_e32 v2, 16, v194
	s_add_u32 s12, s4, 0xaa00000
	v_cmp_lt_i32_e32 vcc, v2, v4
	s_addc_u32 s13, s5, 0
	s_add_u32 s14, s4, 0x9a00000
	v_cndmask_b32_e32 v2, v194, v2, vcc
	v_mov_b32_e32 v11, 0
	v_lshlrev_b32_e32 v24, 2, v2
	v_xor_b32_e32 v2, 32, v194
	v_lshlrev_b32_e32 v10, 1, v0
	s_addc_u32 s15, s5, 0
	v_cmp_lt_i32_e32 vcc, v2, v4
	v_lshl_add_u64 v[8:9], s[4:5], 0, v[10:11]
	s_mov_b64 s[4:5], 0x6200000
	v_cndmask_b32_e32 v2, v194, v2, vcc
	v_lshl_add_u64 v[8:9], v[8:9], 0, s[4:5]
	s_mov_b32 s4, 0x3a27c5ac
	v_lshlrev_b32_e32 v25, 2, v2
	s_mov_b32 s1, s20
	v_or_b32_e32 v2, 64, v0
	v_or_b32_e32 v4, 0x80, v0
	v_or_b32_e32 v6, 0xc0, v0
	v_lshl_add_u64 v[10:11], s[6:7], 0, v[10:11]
	v_mov_b32_e32 v26, 0x380
	s_mov_b32 s16, 0x3c800000
	s_mov_b32 s3, 0x800000
	s_movk_i32 s17, 0x7fff
	v_mov_b64_e32 v[12:13], s[4:5]
.LBB0_1148:
	s_ashr_i32 s4, s2, 2
	s_ashr_i32 s5, s2, 31
	s_lshr_b32 s6, s5, 19
	s_ashr_i32 s5, s4, 31
	s_add_i32 s8, s4, s6
	s_lshl_b64 s[6:7], s[4:5], 8
	v_mov_b32_e32 v29, s7
	v_or_b32_e32 v28, s6, v0
	s_and_b32 s20, s4, 0x1fff
	s_lshl_b64 s[4:5], s[4:5], 11
	s_ashr_i32 s8, s8, 13
	v_mov_b32_e32 v31, s7
	v_or_b32_e32 v30, s6, v2
	v_mov_b32_e32 v33, s7
	v_or_b32_e32 v32, s6, v4
	v_mov_b32_e32 v35, s7
	v_or_b32_e32 v34, s6, v6
	v_lshl_add_u64 v[36:37], v[28:29], 2, s[12:13]
	v_lshl_add_u64 v[14:15], v[10:11], 0, s[4:5]
	s_lshl_b32 s4, s8, 2
	v_lshl_add_u64 v[28:29], v[28:29], 1, s[14:15]
	v_lshl_add_u64 v[38:39], v[30:31], 2, s[12:13]
	v_lshl_add_u64 v[30:31], v[30:31], 1, s[14:15]
	v_lshl_add_u64 v[40:41], v[32:33], 2, s[12:13]
	v_lshl_add_u64 v[32:33], v[32:33], 1, s[14:15]
	v_lshl_add_u64 v[42:43], v[34:35], 2, s[12:13]
	v_lshl_add_u64 v[34:35], v[34:35], 1, s[14:15]
	global_load_dword v45, v[36:37], off
	global_load_ushort v27, v[28:29], off
	global_load_dword v44, v[38:39], off
	global_load_ushort v48, v[30:31], off
	global_load_dword v47, v[40:41], off
	global_load_ushort v49, v[32:33], off
	global_load_dword v46, v[42:43], off
	global_load_ushort v50, v[34:35], off
	s_ashr_i32 s5, s4, 31
	s_or_b32 s6, s4, 1
	s_or_b32 s8, s4, 2
	s_or_b32 s18, s4, 3
	s_lshl_b64 s[4:5], s[4:5], 13
	s_ashr_i32 s7, s6, 31
	s_ashr_i32 s9, s8, 31
	s_ashr_i32 s19, s18, 31
	s_or_b32 s21, s4, s20
	s_mul_i32 s22, s5, 0x380
	s_lshl_b64 s[4:5], s[6:7], 13
	s_lshl_b64 s[6:7], s[8:9], 13
	s_lshl_b64 s[8:9], s[18:19], 13
	v_mad_u64_u32 v[28:29], s[18:19], s21, v26, v[8:9]
	v_add_u32_e32 v29, s22, v29
	global_load_ushort v36, v[28:29], off offset:256
	global_load_ushort v37, v[28:29], off offset:384
	global_load_ushort v40, v[28:29], off offset:512
	s_or_b32 s4, s4, s20
	s_mul_i32 s18, s5, 0x380
	s_or_b32 s6, s6, s20
	s_or_b32 s8, s8, s20
	v_mad_u64_u32 v[30:31], s[4:5], s4, v26, v[8:9]
	s_mulk_i32 s7, 0x380
	s_mulk_i32 s9, 0x380
	v_mad_u64_u32 v[32:33], s[4:5], s6, v26, v[8:9]
	v_mad_u64_u32 v[34:35], s[4:5], s8, v26, v[8:9]
	v_add_u32_e32 v31, s18, v31
	v_add_u32_e32 v33, s7, v33
	v_add_u32_e32 v35, s9, v35
	global_load_ushort v38, v[30:31], off offset:256
	global_load_ushort v39, v[30:31], off offset:384
	global_load_ushort v41, v[32:33], off offset:256
	global_load_ushort v42, v[32:33], off offset:384
	global_load_ushort v43, v[34:35], off offset:256
	global_load_ushort v51, v[34:35], off offset:384
	global_load_ushort v52, v[30:31], off offset:512
	global_load_ushort v53, v[32:33], off offset:512
	global_load_ushort v54, v[34:35], off offset:512
	s_add_i32 s2, s2, s1
	s_cmp_lt_i32 s2, s101
	s_waitcnt vmcnt(19)
	v_mov_b32_dpp v29, v45 quad_perm:[1,0,3,2] row_mask:0xf bank_mask:0xf bound_ctrl:1
	s_waitcnt vmcnt(18)
	v_cvt_f32_f16_e32 v27, v27
	s_waitcnt vmcnt(17)
	v_mov_b32_dpp v28, v44 quad_perm:[1,0,3,2] row_mask:0xf bank_mask:0xf bound_ctrl:1
	v_pk_add_f32 v[28:29], v[44:45], v[28:29]
	s_waitcnt vmcnt(15)
	v_mov_b32_dpp v31, v47 quad_perm:[1,0,3,2] row_mask:0xf bank_mask:0xf bound_ctrl:1
	v_cvt_f32_f16_e32 v48, v48
	s_waitcnt vmcnt(13)
	v_mov_b32_dpp v30, v46 quad_perm:[1,0,3,2] row_mask:0xf bank_mask:0xf bound_ctrl:1
	v_pk_add_f32 v[30:31], v[46:47], v[30:31]
	v_mov_b32_dpp v33, v29 quad_perm:[2,3,0,1] row_mask:0xf bank_mask:0xf bound_ctrl:1
	v_mov_b32_dpp v32, v28 quad_perm:[2,3,0,1] row_mask:0xf bank_mask:0xf bound_ctrl:1
	v_mov_b32_dpp v35, v31 quad_perm:[2,3,0,1] row_mask:0xf bank_mask:0xf bound_ctrl:1
	v_mov_b32_dpp v34, v30 quad_perm:[2,3,0,1] row_mask:0xf bank_mask:0xf bound_ctrl:1
	v_pk_add_f32 v[28:29], v[28:29], v[32:33]
	v_pk_add_f32 v[30:31], v[30:31], v[34:35]
	v_cvt_f32_f16_e32 v49, v49
	v_mov_b32_dpp v33, v29 row_half_mirror row_mask:0xf bank_mask:0xf bound_ctrl:1
	v_mov_b32_dpp v32, v28 row_half_mirror row_mask:0xf bank_mask:0xf bound_ctrl:1
	v_mov_b32_dpp v35, v31 row_half_mirror row_mask:0xf bank_mask:0xf bound_ctrl:1
	v_mov_b32_dpp v34, v30 row_half_mirror row_mask:0xf bank_mask:0xf bound_ctrl:1
	v_pk_add_f32 v[28:29], v[28:29], v[32:33]
	v_pk_add_f32 v[30:31], v[30:31], v[34:35]
	s_waitcnt vmcnt(12)
	v_cvt_f32_f16_e32 v50, v50
	v_mov_b32_dpp v33, v29 row_mirror row_mask:0xf bank_mask:0xf bound_ctrl:1
	v_mov_b32_dpp v32, v28 row_mirror row_mask:0xf bank_mask:0xf bound_ctrl:1
	s_waitcnt vmcnt(11)
	v_cvt_f32_f16_e32 v36, v36
	s_waitcnt vmcnt(10)
	v_cvt_f32_f16_e32 v37, v37
	v_mov_b32_dpp v35, v31 row_mirror row_mask:0xf bank_mask:0xf bound_ctrl:1
	v_mov_b32_dpp v34, v30 row_mirror row_mask:0xf bank_mask:0xf bound_ctrl:1
	v_pk_add_f32 v[28:29], v[28:29], v[32:33]
	v_pk_add_f32 v[30:31], v[30:31], v[34:35]
	ds_bpermute_b32 v33, v24, v29
	ds_bpermute_b32 v32, v24, v28
	s_waitcnt vmcnt(8)
	v_cvt_f32_f16_e32 v38, v38
	s_waitcnt vmcnt(7)
	v_cvt_f32_f16_e32 v39, v39
	s_waitcnt vmcnt(6)
	v_cvt_f32_f16_e32 v41, v41
	s_waitcnt vmcnt(5)
	v_cvt_f32_f16_e32 v42, v42
	s_waitcnt vmcnt(4)
	v_cvt_f32_f16_e32 v43, v43
	s_waitcnt vmcnt(3)
	v_cvt_f32_f16_e32 v51, v51
	ds_bpermute_b32 v35, v24, v31
	ds_bpermute_b32 v34, v24, v30
	v_mul_f32_e32 v36, v36, v37
	v_mul_f32_e32 v37, v17, v36
	v_mul_f32_e32 v38, v38, v39
	v_mul_f32_e32 v39, v41, v42
	v_mul_f32_e32 v41, v43, v51
	v_mov_b32_dpp v37, v37 quad_perm:[1,0,3,2] row_mask:0xf bank_mask:0xf bound_ctrl:1
	v_mul_f32_e32 v42, v19, v38
	s_waitcnt lgkmcnt(2)
	v_pk_add_f32 v[28:29], v[28:29], v[32:33]
	v_mul_f32_e32 v43, v21, v39
	v_mul_f32_e32 v51, v23, v41
	v_fmac_f32_e32 v37, v17, v36
	v_mov_b32_dpp v36, v42 quad_perm:[1,0,3,2] row_mask:0xf bank_mask:0xf bound_ctrl:1
	s_waitcnt lgkmcnt(0)
	v_pk_add_f32 v[30:31], v[30:31], v[34:35]
	ds_bpermute_b32 v33, v25, v29
	ds_bpermute_b32 v32, v25, v28
	v_mov_b32_dpp v42, v43 quad_perm:[1,0,3,2] row_mask:0xf bank_mask:0xf bound_ctrl:1
	v_mov_b32_dpp v43, v51 quad_perm:[1,0,3,2] row_mask:0xf bank_mask:0xf bound_ctrl:1
	v_fmac_f32_e32 v36, v19, v38
	ds_bpermute_b32 v35, v25, v31
	ds_bpermute_b32 v34, v25, v30
	v_add_f32_dpp v37, v37, v37 quad_perm:[2,3,0,1] row_mask:0xf bank_mask:0xf bound_ctrl:1
	v_fmac_f32_e32 v42, v21, v39
	v_fmac_f32_e32 v43, v23, v41
	v_add_f32_dpp v36, v36, v36 quad_perm:[2,3,0,1] row_mask:0xf bank_mask:0xf bound_ctrl:1
	v_add_f32_dpp v37, v37, v37 row_half_mirror row_mask:0xf bank_mask:0xf bound_ctrl:1
	v_add_f32_dpp v38, v42, v42 quad_perm:[2,3,0,1] row_mask:0xf bank_mask:0xf bound_ctrl:1
	v_add_f32_dpp v39, v43, v43 quad_perm:[2,3,0,1] row_mask:0xf bank_mask:0xf bound_ctrl:1
	v_add_f32_dpp v36, v36, v36 row_half_mirror row_mask:0xf bank_mask:0xf bound_ctrl:1
	v_add_f32_dpp v37, v37, v37 row_mirror row_mask:0xf bank_mask:0xf bound_ctrl:1
	v_add_f32_dpp v38, v38, v38 row_half_mirror row_mask:0xf bank_mask:0xf bound_ctrl:1
	v_add_f32_dpp v39, v39, v39 row_half_mirror row_mask:0xf bank_mask:0xf bound_ctrl:1
	v_add_f32_dpp v36, v36, v36 row_mirror row_mask:0xf bank_mask:0xf bound_ctrl:1
	ds_bpermute_b32 v41, v24, v37
	v_add_f32_dpp v38, v38, v38 row_mirror row_mask:0xf bank_mask:0xf bound_ctrl:1
	v_add_f32_dpp v39, v39, v39 row_mirror row_mask:0xf bank_mask:0xf bound_ctrl:1
	ds_bpermute_b32 v42, v24, v36
	s_waitcnt lgkmcnt(4)
	v_pk_add_f32 v[28:29], v[28:29], v[32:33]
	ds_bpermute_b32 v43, v24, v38
	ds_bpermute_b32 v51, v24, v39
	s_waitcnt lgkmcnt(4)
	v_pk_add_f32 v[30:31], v[30:31], v[34:35]
	v_pk_fma_f32 v[28:29], v[28:29], s[16:17], v[44:45] op_sel_hi:[1,0,1] neg_lo:[1,0,0] neg_hi:[1,0,0]
	v_pk_fma_f32 v[30:31], v[30:31], s[16:17], v[46:47] op_sel_hi:[1,0,1] neg_lo:[1,0,0] neg_hi:[1,0,0]
	v_pk_mul_f32 v[32:33], v[28:29], v[28:29]
	v_pk_mul_f32 v[34:35], v[30:31], v[30:31]
	s_waitcnt lgkmcnt(3)
	v_add_f32_e32 v41, v37, v41
	v_mov_b32_dpp v33, v33 quad_perm:[1,0,3,2] row_mask:0xf bank_mask:0xf bound_ctrl:1
	v_mov_b32_dpp v32, v32 quad_perm:[1,0,3,2] row_mask:0xf bank_mask:0xf bound_ctrl:1
	v_mov_b32_dpp v35, v35 quad_perm:[1,0,3,2] row_mask:0xf bank_mask:0xf bound_ctrl:1
	v_mov_b32_dpp v34, v34 quad_perm:[1,0,3,2] row_mask:0xf bank_mask:0xf bound_ctrl:1
	v_pk_fma_f32 v[32:33], v[28:29], v[28:29], v[32:33]
	s_waitcnt lgkmcnt(2)
	v_add_f32_e32 v42, v36, v42
	v_pk_fma_f32 v[34:35], v[30:31], v[30:31], v[34:35]
	v_mov_b32_dpp v37, v33 quad_perm:[2,3,0,1] row_mask:0xf bank_mask:0xf bound_ctrl:1
	v_mov_b32_dpp v36, v32 quad_perm:[2,3,0,1] row_mask:0xf bank_mask:0xf bound_ctrl:1
	s_waitcnt lgkmcnt(1)
	v_add_f32_e32 v43, v38, v43
	s_waitcnt lgkmcnt(0)
	v_add_f32_e32 v45, v39, v51
	v_mov_b32_dpp v39, v35 quad_perm:[2,3,0,1] row_mask:0xf bank_mask:0xf bound_ctrl:1
	v_mov_b32_dpp v38, v34 quad_perm:[2,3,0,1] row_mask:0xf bank_mask:0xf bound_ctrl:1
	v_pk_add_f32 v[32:33], v[32:33], v[36:37]
	v_pk_add_f32 v[34:35], v[34:35], v[38:39]
	ds_bpermute_b32 v44, v25, v41
	v_mov_b32_dpp v37, v33 row_half_mirror row_mask:0xf bank_mask:0xf bound_ctrl:1
	v_mov_b32_dpp v36, v32 row_half_mirror row_mask:0xf bank_mask:0xf bound_ctrl:1
	v_mov_b32_dpp v39, v35 row_half_mirror row_mask:0xf bank_mask:0xf bound_ctrl:1
	v_mov_b32_dpp v38, v34 row_half_mirror row_mask:0xf bank_mask:0xf bound_ctrl:1
	v_pk_add_f32 v[32:33], v[32:33], v[36:37]
	v_pk_add_f32 v[34:35], v[34:35], v[38:39]
	ds_bpermute_b32 v46, v25, v42
	v_mov_b32_dpp v37, v33 row_mirror row_mask:0xf bank_mask:0xf bound_ctrl:1
	v_mov_b32_dpp v36, v32 row_mirror row_mask:0xf bank_mask:0xf bound_ctrl:1
	v_mov_b32_dpp v39, v35 row_mirror row_mask:0xf bank_mask:0xf bound_ctrl:1
	v_mov_b32_dpp v38, v34 row_mirror row_mask:0xf bank_mask:0xf bound_ctrl:1
	v_pk_add_f32 v[32:33], v[32:33], v[36:37]
	v_pk_add_f32 v[34:35], v[34:35], v[38:39]
	ds_bpermute_b32 v37, v24, v33
	ds_bpermute_b32 v36, v24, v32
	ds_bpermute_b32 v39, v24, v35
	ds_bpermute_b32 v38, v24, v34
	ds_bpermute_b32 v47, v25, v43
	ds_bpermute_b32 v51, v25, v45
	s_waitcnt lgkmcnt(4)
	v_pk_add_f32 v[32:33], v[32:33], v[36:37]
	ds_bpermute_b32 v37, v25, v33
	s_waitcnt lgkmcnt(3)
	v_pk_add_f32 v[34:35], v[34:35], v[38:39]
	ds_bpermute_b32 v36, v25, v32
	ds_bpermute_b32 v39, v25, v35
	ds_bpermute_b32 v38, v25, v34
	v_add_f32_e32 v41, v41, v44
	v_add_f32_e32 v42, v42, v46
	s_waitcnt lgkmcnt(2)
	v_pk_add_f32 v[32:33], v[32:33], v[36:37]
	v_add_f32_e32 v43, v43, v47
	s_waitcnt lgkmcnt(0)
	v_pk_add_f32 v[34:35], v[34:35], v[38:39]
	v_pk_fma_f32 v[32:33], v[32:33], s[16:17], v[12:13] op_sel_hi:[1,0,0]
	v_pk_fma_f32 v[34:35], v[34:35], s[16:17], v[12:13] op_sel_hi:[1,0,0]
	v_mul_f32_e32 v36, 0x4b800000, v33
	v_cmp_gt_f32_e64 s[8:9], s3, v33
	v_mul_f32_e32 v37, 0x4b800000, v32
	v_cmp_gt_f32_e32 vcc, s3, v32
	v_mul_f32_e32 v38, 0x4b800000, v35
	v_mul_f32_e32 v39, 0x4b800000, v34
	v_cmp_gt_f32_e64 s[4:5], s3, v34
	v_cmp_gt_f32_e64 s[6:7], s3, v35
	v_cndmask_b32_e64 v33, v33, v36, s[8:9]
	v_cndmask_b32_e32 v32, v32, v37, vcc
	v_cndmask_b32_e64 v35, v35, v38, s[6:7]
	v_cndmask_b32_e64 v34, v34, v39, s[4:5]
	v_rsq_f32_e32 v33, v33
	v_rsq_f32_e32 v32, v32
	v_rsq_f32_e32 v35, v35
	v_rsq_f32_e32 v34, v34
	v_mul_f32_e32 v36, 0x45800000, v33
	v_mul_f32_e32 v37, 0x45800000, v32
	v_mul_f32_e32 v38, 0x45800000, v35
	v_mul_f32_e32 v39, 0x45800000, v34
	v_cndmask_b32_e64 v33, v33, v36, s[8:9]
	v_cndmask_b32_e32 v32, v32, v37, vcc
	v_cndmask_b32_e64 v35, v35, v38, s[6:7]
	v_cndmask_b32_e64 v34, v34, v39, s[4:5]
	v_mul_f32_e32 v29, v29, v33
	v_mul_f32_e32 v28, v28, v32
	v_mul_f32_e32 v31, v31, v35
	v_mul_f32_e32 v30, v30, v34
	v_fma_f32 v29, v16, v29, v1
	v_add_f32_e32 v44, v45, v51
	v_fma_f32 v28, v18, v28, v3
	v_fma_f32 v31, v20, v31, v5
	v_fma_f32 v30, v22, v30, v7
	v_fma_mix_f32 v29, v41, v40, v29 op_sel_hi:[0,1,0]
	s_waitcnt vmcnt(2)
	v_fma_mix_f32 v28, v42, v52, v28 op_sel_hi:[0,1,0]
	s_waitcnt vmcnt(1)
	v_fma_mix_f32 v31, v43, v53, v31 op_sel_hi:[0,1,0]
	s_waitcnt vmcnt(0)
	v_fma_mix_f32 v30, v44, v54, v30 op_sel_hi:[0,1,0]
	v_mul_f32_e32 v27, v29, v27
	v_mul_f32_e32 v28, v28, v48
	v_mul_f32_e32 v29, v31, v49
	v_mul_f32_e32 v30, v30, v50
	v_bfe_u32 v31, v27, 16, 1
	v_bfe_u32 v32, v28, 16, 1
	v_bfe_u32 v33, v29, 16, 1
	v_bfe_u32 v34, v30, 16, 1
	v_add3_u32 v27, v27, v31, s17
	v_add3_u32 v28, v28, v32, s17
	v_add3_u32 v29, v29, v33, s17
	v_add3_u32 v30, v30, v34, s17
	global_store_short_d16_hi v[14:15], v27, off offset:1024
	global_store_short_d16_hi v[14:15], v28, off offset:1152
	global_store_short_d16_hi v[14:15], v29, off offset:1280
	global_store_short_d16_hi v[14:15], v30, off offset:1408
	s_cbranch_scc1 .LBB0_1148

.LBB0_2852:
	s_lshl_b32 s2, s2, 5
	s_lshl_b32 s3, s3, 2
	s_add_i32 s2, s3, s2
	s_cmp_lt_u32 s90, 64
	s_movk_i32 s20, 0x1800
	s_mov_b32 s101, 0x10000
	s_cselect_b32 s20, 0x800, s20
	s_cselect_b32 s101, 0x2000, s101
	s_cselect_b32 s21, 0, 0x1800
	s_add_i32 s2, s2, s21
	s_cmp_gt_i32 s2, 0xffff
	s_cbranch_scc1 .LBB0_2855
	s_load_dwordx2 s[16:17], s[8:9], 0x100
	s_load_dwordx4 s[12:15], s[8:9], 0xf0
	v_and_b32_e32 v0, 63, v195
	v_lshlrev_b32_e32 v2, 2, v0
	v_and_b32_e32 v4, 64, v194
	v_add_u32_e32 v4, 64, v4
	s_waitcnt lgkmcnt(0)
	global_load_dword v1, v2, s[16:17] offset:1024
	global_load_dword v3, v2, s[16:17] offset:1280
	global_load_dword v5, v2, s[16:17] offset:1536
	global_load_dword v7, v2, s[16:17] offset:1792
	global_load_dword v16, v2, s[14:15] offset:1024
	global_load_dword v17, v2, s[12:13] offset:1024
	global_load_dword v18, v2, s[14:15] offset:1280
	global_load_dword v19, v2, s[12:13] offset:1280
	global_load_dword v20, v2, s[14:15] offset:1536
	global_load_dword v21, v2, s[12:13] offset:1536
	global_load_dword v22, v2, s[14:15] offset:1792
	global_load_dword v23, v2, s[12:13] offset:1792
	v_xor_b32_e32 v2, 16, v194
	s_add_u32 s12, s4, 0xaa00000
	v_cmp_lt_i32_e32 vcc, v2, v4
	s_addc_u32 s13, s5, 0
	s_add_u32 s14, s4, 0x9a00000
	v_cndmask_b32_e32 v2, v194, v2, vcc
	v_mov_b32_e32 v11, 0
	v_lshlrev_b32_e32 v24, 2, v2
	v_xor_b32_e32 v2, 32, v194
	v_lshlrev_b32_e32 v10, 1, v0
	s_addc_u32 s15, s5, 0
	v_cmp_lt_i32_e32 vcc, v2, v4
	v_lshl_add_u64 v[8:9], s[4:5], 0, v[10:11]
	s_mov_b64 s[4:5], 0x6200000
	v_cndmask_b32_e32 v2, v194, v2, vcc
	v_lshl_add_u64 v[8:9], v[8:9], 0, s[4:5]
	s_mov_b32 s4, 0x3a27c5ac
	v_lshlrev_b32_e32 v25, 2, v2
	s_mov_b32 s1, s20
	v_or_b32_e32 v2, 64, v0
	v_or_b32_e32 v4, 0x80, v0
	v_or_b32_e32 v6, 0xc0, v0
	v_lshl_add_u64 v[10:11], s[6:7], 0, v[10:11]
	v_mov_b32_e32 v26, 0x380
	s_mov_b32 s16, 0x3c800000
	s_mov_b32 s3, 0x800000
	s_movk_i32 s17, 0x7fff
	v_mov_b64_e32 v[12:13], s[4:5]
